# v48 + in-proj (layer 1) 32-unit groups permuted so every XCD gets a mix of unit kinds
# speedup vs baseline: 1.0098x; 1.0035x over previous
;     __device__ __forceinline__ bool next(int i, Unit& u) const {
;         int q, hf; if (!L.idx(i, q, hf)) return false;
;         const char* H = (const char*)(ws + OFF_HY);
;         u.p1 = nullptr; u.p2 = nullptr; u.nt = 16; u.mode = 0; u.half = 0; u.mk = -1; u.mneg = 0;
;         int kind, pm, pn, bt = 0;
;         if (!l1) { if (q < 504) { kind = 0; const int gid = q / 56, rem = q % 56; pm = gid * 8 + (rem & 7); pn = rem >> 3; } else if (q < 760) { const int s = q - 504; kind = 1; bt = s >> 5; pn = (s & 31) >> 2; pm = s & 3; } else { const int s = q - 760; kind = 2; bt = s >> 2; pm = s & 3; pn = 0; } }
;         else { if (q < 448) { kind = 0; const int gid = q / 56, rem = q % 56; pm = gid * 8 + (rem & 7); pn = rem >> 3; } else if (q < 488) { const int s = q - 448, r5 = s % 5; kind = 0; pm = 64 + s / 5; pn = r5 < 4 ? r5 + 1 : 6; }
;                else if (q < 744) { const int s = q - 488; kind = 1; bt = s >> 5; pn = (s & 31) >> 2; pm = s & 3; } else { const int s = q - 744; kind = 2; bt = s / 3; pm = 1 + s % 3; pn = 0; } }
.LBB0_375:
	v_readlane_b32 s10, v255, 20
	v_readlane_b32 s11, v255, 21
	s_mov_b64 s[4:5], -1
	s_and_b64 vcc, exec, s[10:11]
	s_cbranch_vccz .LBB0_387
	s_lshr_b32 s18, s19, 5
	s_mul_i32 s20, s18, 11
	s_lshr_b32 s20, s20, 5
	s_mul_i32 s22, s20, 3
	s_sub_i32 s22, s18, s22
	s_lshl_b32 s23, s20, 1
	s_add_i32 s23, s23, s22
	s_cmp_lt_u32 s20, 6
	s_cbranch_scc0 .Lperm_hi_a
	s_add_i32 s18, s20, 14
	s_cmp_lt_u32 s22, 2
	s_cselect_b32 s23, s23, s18
	s_branch .Lperm_done_a
.Lperm_hi_a:
	s_add_i32 s18, s20, 6
	s_add_i32 s23, s23, 7
	s_cmp_eq_u32 s22, 0
	s_cselect_b32 s23, s18, s23
.Lperm_done_a:
	s_and_b32 s19, s19, 31
	s_lshl_b32 s23, s23, 5
	s_or_b32 s19, s19, s23
	s_cmpk_gt_i32 s19, 0x1bf
	s_mov_b64 s[14:15], -1
	s_cbranch_scc0 .LBB0_384
	s_cmpk_gt_u32 s19, 0x1e7
	s_cbranch_scc0 .LBB0_382
	s_cmpk_gt_u32 s19, 0x2e7
	s_mov_b64 s[10:11], -1
	s_cbranch_scc0 .LBB0_380
	s_add_i32 s3, s19, 0xfffffd18
	s_mul_hi_u32 s4, s3, 0xaaaaaaab
	s_lshr_b32 s56, s4, 1
	s_mul_i32 s4, s56, 3
	s_sub_i32 s3, s3, s4
	s_add_i32 s18, s3, 1
	s_mov_b64 s[10:11], 0

;     __device__ __forceinline__ bool next(int i, Unit& u) const {
;         int q, hf; if (!L.idx(i, q, hf)) return false;
;         const char* H = (const char*)(ws + OFF_HY);
;         u.p1 = nullptr; u.p2 = nullptr; u.nt = 16; u.mode = 0; u.half = 0; u.mk = -1; u.mneg = 0;
;         int kind, pm, pn, bt = 0;
;         if (!l1) { if (q < 504) { kind = 0; const int gid = q / 56, rem = q % 56; pm = gid * 8 + (rem & 7); pn = rem >> 3; } else if (q < 760) { const int s = q - 504; kind = 1; bt = s >> 5; pn = (s & 31) >> 2; pm = s & 3; } else { const int s = q - 760; kind = 2; bt = s >> 2; pm = s & 3; pn = 0; } }
;         else { if (q < 448) { kind = 0; const int gid = q / 56, rem = q % 56; pm = gid * 8 + (rem & 7); pn = rem >> 3; } else if (q < 488) { const int s = q - 448, r5 = s % 5; kind = 0; pm = 64 + s / 5; pn = r5 < 4 ? r5 + 1 : 6; }
;                else if (q < 744) { const int s = q - 488; kind = 1; bt = s >> 5; pn = (s & 31) >> 2; pm = s & 3; } else { const int s = q - 744; kind = 2; bt = s / 3; pm = 1 + s % 3; pn = 0; } }
.LBB0_415:
	s_xor_b64 s[26:27], s[30:31], -1
	s_and_b64 vcc, exec, s[26:27]
	s_mov_b64 s[36:37], s[14:15]
	s_mov_b64 s[34:35], s[10:11]
	s_cbranch_vccnz .LBB0_446
	v_readlane_b32 s12, v255, 20
	v_readlane_b32 s13, v255, 21
	s_mov_b64 s[4:5], -1
	s_and_b64 vcc, exec, s[12:13]
	s_cbranch_vccz .LBB0_428
	s_lshr_b32 s8, s9, 5
	s_mul_i32 s28, s8, 11
	s_lshr_b32 s28, s28, 5
	s_mul_i32 s38, s28, 3
	s_sub_i32 s38, s8, s38
	s_lshl_b32 s39, s28, 1
	s_add_i32 s39, s39, s38
	s_cmp_lt_u32 s28, 6
	s_cbranch_scc0 .Lperm_hi_b
	s_add_i32 s8, s28, 14
	s_cmp_lt_u32 s38, 2
	s_cselect_b32 s39, s39, s8
	s_branch .Lperm_done_b
.Lperm_hi_b:
	s_add_i32 s8, s28, 6
	s_add_i32 s39, s39, 7
	s_cmp_eq_u32 s38, 0
	s_cselect_b32 s39, s8, s39
.Lperm_done_b:
	s_and_b32 s9, s9, 31
	s_lshl_b32 s39, s39, 5
	s_or_b32 s9, s9, s39
	s_cmpk_gt_i32 s9, 0x1bf
	s_mov_b64 s[34:35], -1
	s_cbranch_scc0 .LBB0_425
	s_cmpk_gt_u32 s9, 0x1e7
	s_cbranch_scc0 .LBB0_423
	s_cmpk_gt_u32 s9, 0x2e7
	s_mov_b64 s[28:29], -1
	s_cbranch_scc0 .LBB0_421
	s_add_i32 s4, s9, 0xfffffd18
	s_mul_hi_u32 s5, s4, 0xaaaaaaab
	s_lshr_b32 s56, s5, 1
	s_mul_i32 s5, s56, 3
	s_sub_i32 s4, s4, s5
	s_add_i32 s8, s4, 1
	s_mov_b64 s[28:29], 0
